# stack6 plus SGU row-statistics loop: row loads issued one row ahead, wave sums by DPP row operations
# baseline (speedup 1.0000x reference)
; __device__ __forceinline__ void sgu_chunk(const Ctx& C, const Args& a, int l, int n) {
;     ...
;     const size_t R0 = (size_t)n * 128; const int lane = C.lane, wid = C.wave, r32 = lane & 31, hi = lane >> 5;
;     for (int rr = 0; rr < 16; ++rr) { const int r = wid * 16 + rr; const u32x4* p = (const u32x4*)(VB + (R0 + r) * D); const u32x4 a0 = p[lane], a1 = p[64 + lane];
.LBB0_149:
	s_mov_b32 s36, 0
	v_mov_b64_e32 v[0:1], v[40:41]
	s_mov_b64 s[100:101], 0x800
	global_load_dwordx4 v[178:181], v[40:41], off
	global_load_dwordx4 v[182:185], v[40:41], off offset:1024
	s_branch .LBB0_151

; __device__ __forceinline__ float bf_lo(unsigned w) { return __uint_as_float(w << 16); }
; __device__ __forceinline__ float bf_hi(unsigned w) { return __uint_as_float(w & 0xffff0000u); }
; __device__ __forceinline__ void sgu_chunk(const Ctx& C, const Args& a, int l, int n) {
;     ...
;     for (int rr = 0; rr < 16; ++rr) { const int r = wid * 16 + rr; const u32x4* p = (const u32x4*)(VB + (R0 + r) * D); const u32x4 a0 = p[lane], a1 = p[64 + lane];
;         float s = 0.f, s2 = 0.f;
; #pragma unroll
;         for (int k = 0; k < 4; ++k) { const float x0 = bf_lo(a0[k]), x1 = bf_hi(a0[k]), x2 = bf_lo(a1[k]), x3 = bf_hi(a1[k]); s += (x0 + x1) + (x2 + x3); s2 += (x0 * x0 + x1 * x1) + (x2 * x2 + x3 * x3); }
;         s = wave_sum(s); s2 = wave_sum(s2); const float mean = s * (1.f / D); const float var = fmaxf(s2 * (1.f / D) - mean * mean, 0.f);
;         if (lane == 0) stats[r] = (f32x2){mean, 1.f / sqrtf(var + LN_EPS)}; }
.LBB0_151:
	s_waitcnt lgkmcnt(0)
	s_waitcnt vmcnt(0)
	v_mov_b32_e32 v2, v178
	v_mov_b32_e32 v3, v179
	v_mov_b32_e32 v4, v180
	v_mov_b32_e32 v5, v181
	v_mov_b32_e32 v6, v182
	v_mov_b32_e32 v7, v183
	v_mov_b32_e32 v8, v184
	v_mov_b32_e32 v9, v185
	v_lshl_add_u64 v[186:187], v[0:1], 0, s[100:101]
	global_load_dwordx4 v[178:181], v[186:187], off
	global_load_dwordx4 v[182:185], v[186:187], off offset:1024
	v_and_b32_e32 v11, 0xffff0000, v2
	v_lshlrev_b32_e32 v10, 16, v6
	v_and_b32_e32 v12, 0xffff0000, v6
	v_and_b32_e32 v13, 0xffff0000, v3
	v_lshlrev_b32_e32 v3, 16, v3
	v_lshlrev_b32_e32 v2, 16, v2
	v_add_f32_e32 v27, v10, v12
	v_mul_f32_e32 v10, v10, v10
	v_lshlrev_b32_e32 v6, 16, v7
	v_and_b32_e32 v7, 0xffff0000, v7
	v_mov_b32_e32 v32, v3
	v_pk_add_f32 v[34:35], v[2:3], v[10:11] op_sel:[1,0] op_sel_hi:[0,1]
	v_mul_f32_e32 v30, v2, v2
	v_mul_f32_e32 v34, v7, v7
	v_mov_b32_e32 v31, v3
	v_pk_mul_f32 v[2:3], v[2:3], v[32:33] op_sel:[1,0] op_sel_hi:[0,1]
	v_lshlrev_b32_e32 v15, 16, v4
	v_and_b32_e32 v17, 0xffff0000, v4
	v_lshlrev_b32_e32 v19, 16, v8
	v_and_b32_e32 v21, 0xffff0000, v8
	v_mul_f32_e32 v28, v12, v12
	v_mul_f32_e32 v26, v13, v13
	v_mul_f32_e32 v12, v11, v11
	v_mov_b32_e32 v11, v6
	v_mov_b32_e32 v29, v7
	v_pk_fma_f32 v[6:7], v[6:7], v[6:7], v[34:35] op_sel_hi:[1,1,0]
	v_mov_b32_e32 v3, v35
	v_lshlrev_b32_e32 v23, 16, v5
	v_and_b32_e32 v5, 0xffff0000, v5
	v_lshlrev_b32_e32 v25, 16, v9
	v_and_b32_e32 v9, 0xffff0000, v9
	v_mul_f32_e32 v14, v15, v15
	v_mul_f32_e32 v16, v17, v17
	v_mul_f32_e32 v18, v19, v19
	v_mul_f32_e32 v20, v21, v21
	v_pk_add_f32 v[12:13], v[30:31], v[12:13]
	v_pk_add_f32 v[10:11], v[10:11], v[28:29]
	v_mov_b32_e32 v7, v193
	v_pk_add_f32 v[2:3], v[2:3], v[26:27]
	v_mul_f32_e32 v22, v23, v23
	v_mul_f32_e32 v4, v5, v5
	v_mul_f32_e32 v24, v25, v25
	v_mul_f32_e32 v8, v9, v9
	v_pk_add_f32 v[14:15], v[14:15], v[16:17]
	v_pk_add_f32 v[16:17], v[18:19], v[20:21]
	v_pk_add_f32 v[10:11], v[12:13], v[10:11]
	v_pk_add_f32 v[2:3], v[2:3], v[6:7]
	v_pk_add_f32 v[4:5], v[22:23], v[4:5]
	v_pk_add_f32 v[8:9], v[24:25], v[8:9]
	v_pk_add_f32 v[12:13], v[14:15], v[16:17]
	v_pk_add_f32 v[2:3], v[10:11], v[2:3]
	v_pk_add_f32 v[4:5], v[4:5], v[8:9]
	v_pk_add_f32 v[2:3], v[12:13], v[2:3]
	s_nop 0
	v_pk_add_f32 v[2:3], v[4:5], v[2:3]
	s_nop 1
	v_add_f32_dpp v2, v2, v2 quad_perm:[1,0,3,2] row_mask:0xf bank_mask:0xf
	v_add_f32_dpp v3, v3, v3 quad_perm:[1,0,3,2] row_mask:0xf bank_mask:0xf
	s_nop 0
	v_add_f32_dpp v2, v2, v2 quad_perm:[2,3,0,1] row_mask:0xf bank_mask:0xf
	v_add_f32_dpp v3, v3, v3 quad_perm:[2,3,0,1] row_mask:0xf bank_mask:0xf
	s_nop 0
	v_add_f32_dpp v2, v2, v2 row_half_mirror row_mask:0xf bank_mask:0xf
	v_add_f32_dpp v3, v3, v3 row_half_mirror row_mask:0xf bank_mask:0xf
	s_nop 0
	v_add_f32_dpp v2, v2, v2 row_mirror row_mask:0xf bank_mask:0xf
	v_add_f32_dpp v3, v3, v3 row_mirror row_mask:0xf bank_mask:0xf
	s_nop 0
	v_add_f32_dpp v2, v2, v2 row_bcast:15 row_mask:0xa bank_mask:0xf
	v_add_f32_dpp v3, v3, v3 row_bcast:15 row_mask:0xa bank_mask:0xf
	s_nop 0
	v_add_f32_dpp v2, v2, v2 row_bcast:31 row_mask:0xc bank_mask:0xf
	v_add_f32_dpp v3, v3, v3 row_bcast:31 row_mask:0xc bank_mask:0xf
	s_nop 0
	v_readlane_b32 s98, v2, 63
	v_readlane_b32 s99, v3, 63
	s_and_saveexec_b64 s[18:19], s[42:43]
	s_cbranch_execz .LBB0_150
	v_mov_b32_e32 v2, s98
	v_mov_b32_e32 v3, s99
	s_mov_b32 s44, 0x3a800000
	v_pk_mul_f32 v[2:3], v[2:3], s[44:45] op_sel_hi:[1,0]
	s_add_i32 s12, s28, s36
	v_fma_f32 v2, -v3, v3, v2
	v_max_f32_e32 v2, 0, v2
	v_add_f32_e32 v2, 0x3727c5ac, v2
	v_mul_f32_e32 v4, 0x4f800000, v2
	v_cmp_gt_f32_e32 vcc, s10, v2
	s_nop 1
	v_cndmask_b32_e32 v2, v2, v4, vcc
	v_sqrt_f32_e32 v4, v2
	s_nop 0
	v_add_u32_e32 v5, -1, v4
	v_fma_f32 v7, -v5, v4, v2
	v_add_u32_e32 v6, 1, v4
	v_cmp_ge_f32_e64 s[44:45], 0, v7
	s_nop 1
	v_cndmask_b32_e64 v5, v4, v5, s[44:45]
	v_fma_f32 v4, -v6, v4, v2
	v_cmp_lt_f32_e64 s[44:45], 0, v4
	s_nop 1
	v_cndmask_b32_e64 v4, v5, v6, s[44:45]
	v_mul_f32_e32 v5, 0x37800000, v4
	v_cndmask_b32_e32 v4, v4, v5, vcc
	v_cmp_class_f32_e32 vcc, v2, v224
	s_nop 1
	v_cndmask_b32_e32 v2, v4, v2, vcc
	v_div_scale_f32 v4, s[44:45], v2, v2, 1.0
	v_rcp_f32_e32 v5, v4
	s_nop 0
	v_fma_f32 v6, -v4, v5, 1.0
	v_fmac_f32_e32 v5, v6, v5
	v_div_scale_f32 v6, vcc, 1.0, v2, 1.0
	v_mul_f32_e32 v7, v6, v5
	v_fma_f32 v8, -v4, v7, v6
	v_fmac_f32_e32 v7, v8, v5
	v_fma_f32 v4, -v4, v7, v6
	v_div_fmas_f32 v4, v4, v5, v7
	v_div_fixup_f32 v5, v4, v2, 1.0
	v_mov_b32_e32 v4, v3
	v_mov_b32_e32 v2, s12
	ds_write_b64 v2, v[4:5]
	s_branch .LBB0_150
